# scan A and C: first half of the workgroup's next 128-token chunk requested while the second half of the current one is being scanned
# speedup vs baseline: 1.0034x; 1.0034x over previous
; template <bool PROJECT> ...
;     ...
;     const int utt = lane >> 2, ucc = (lane & 3) * 4;
;     f32x4 uh[4];
; #pragma unroll
;     for (int i = 0; i < 4; ++i) { uh[i] = (f32x4){0.f, 0.f, 0.f, 0.f}; if (16 * i + utt < ntok) uh[i] = *(const f32x4*)(ubuf + (size_t)(row0 + 16 * i + utt) * D + g * 16 + ucc); }
;     const int nhalf = ntok > 64 ? 2 : 1;
; __global__ void __launch_bounds__(NTHREADS, 2) fwd_megakernel(Args a) {
;     ...
;         bf16x8 bop[2][4], cop[4]; float lre = 0.f, lim = 0.f, dv = 0.f; int gcur = -1;
; #pragma unroll 1
;         for (int it = blockIdx.x; it < 1024; it += gridDim.x) {
;             const int g = it & 63, cc = it >> 6, ccp = ((cc & 3) << 2) | (cc >> 2), b = ccp >> 3, co = ccp & 7, k = co * 8 + wave;
;             float hre = 0.f, him = 0.f;
;             scan_run<false>(lds, wave, lane, ubuf, b * SEQ + k * 128, 128, g, lamb + (g * 64 + lane) * 4, bbb + (g * 64 + lane) * 32, nullptr, nullptr, nullptr, nullptr, hre, him, g != gcur, bop, cop, lre, lim, dv);
.LBB0_1456:
	s_or_b64 exec, exec, s[28:29]
	s_load_dwordx2 s[30:31], s[0:1], 0xd0
	s_waitcnt lgkmcnt(0)
	v_lshlrev_b32_e32 v0, 7, v192
	v_and_b32_e32 v71, 8, v154
	v_mov_b32_e32 v48, 0
	v_sub_co_u32_e32 v2, vcc, s30, v0
	v_mov_b32_e32 v0, s31
	s_add_u32 s36, s30, 0x154fc000
	s_barrier
	v_subbrev_co_u32_e32 v3, vcc, 0, v0, vcc
	v_lshlrev_b32_e32 v0, 2, v71
	v_mov_b32_e32 v1, v48
	s_load_dwordx4 s[48:51], s[0:1], 0x98
	s_load_dwordx2 s[40:41], s[0:1], 0xc8
	s_addc_u32 s37, s31, 0
	v_lshl_add_u64 v[2:3], v[2:3], 0, v[0:1]
	v_lshlrev_b32_e32 v4, 7, v161
	v_mov_b32_e32 v5, v48
	s_cmpk_lt_i32 s2, 0x400
	s_mul_i32 s42, s67, 0x4180
	v_lshl_add_u64 v[2:3], v[2:3], 0, v[4:5]
	s_mov_b64 s[6:7], 0x1550c000
	v_lshlrev_b32_e32 v166, 3, v192
	v_mov_b32_e32 v167, v48
	s_cselect_b64 s[38:39], -1, 0
	s_add_i32 s27, s42, 0
	v_lshl_add_u64 v[172:173], v[2:3], 0, s[6:7]
	v_lshl_add_u64 v[2:3], s[30:31], 0, v[166:167]
	s_mov_b64 s[6:7], 0x150fc000
	s_mov_b32 s29, 0
	s_cmpk_gt_i32 s2, 0x3ff
	v_lshl_add_u32 v72, v165, 6, s27
	v_lshlrev_b32_e32 v70, 6, v161
	v_cmp_gt_u32_e64 s[46:47], 32, v192
	v_lshl_add_u32 v169, v161, 3, s27
	v_mul_u32_u24_e32 v171, 0x820, v153
	v_lshl_add_u64 v[174:175], v[2:3], 0, s[6:7]
	s_cbranch_scc1 .LBB0_1467
	v_lshlrev_b32_e32 v1, 4, v160
	v_and_b32_e32 v2, 48, v1
	v_mov_b32_e32 v3, v48
	v_mov_b32_e32 v49, v48
	v_lshl_add_u64 v[50:51], s[24:25], 0, v[2:3]
	v_add_u32_e32 v73, v72, v2
	v_add3_u32 v74, s27, v0, v70
	s_mov_b32 s4, -1
	s_mov_b32 s26, s2
	v_mov_b64_e32 v[52:53], v[48:49]
	v_mov_b32_e32 v0, 0
	v_mov_b32_e32 v1, v48
	v_mov_b32_e32 v2, v48
	v_mov_b32_e32 v8, v48
	v_mov_b32_e32 v9, v48
	v_mov_b32_e32 v10, v48
	v_mov_b32_e32 v11, v48
	v_mov_b32_e32 v16, v48
	v_mov_b32_e32 v17, v48
	v_mov_b32_e32 v18, v48
	v_mov_b32_e32 v19, v48
	v_mov_b32_e32 v24, v48
	v_mov_b32_e32 v25, v48
	v_mov_b32_e32 v26, v48
	v_mov_b32_e32 v27, v48
	v_mov_b32_e32 v4, 0
	v_mov_b32_e32 v5, v48
	v_mov_b32_e32 v6, v48
	v_mov_b32_e32 v7, v48
	v_mov_b32_e32 v12, v48
	v_mov_b32_e32 v13, v48
	v_mov_b32_e32 v14, v48
	v_mov_b32_e32 v15, v48
	v_mov_b32_e32 v20, v48
	v_mov_b32_e32 v21, v48
	v_mov_b32_e32 v22, v48
	v_mov_b32_e32 v23, v48
	v_mov_b32_e32 v28, v48
	v_mov_b32_e32 v29, v48
	v_mov_b32_e32 v30, v48
	v_mov_b32_e32 v31, v48
	s_mov_b32 s99, 0

; #define LAS __attribute__((address_space(3)))
; template <bool PROJECT> ...
;     ...
;     const int utt = lane >> 2, ucc = (lane & 3) * 4;
;     f32x4 uh[4];
; #pragma unroll
;     for (int i = 0; i < 4; ++i) { uh[i] = (f32x4){0.f, 0.f, 0.f, 0.f}; if (16 * i + utt < ntok) uh[i] = *(const f32x4*)(ubuf + (size_t)(row0 + 16 * i + utt) * D + g * 16 + ucc); }
;     const int nhalf = ntok > 64 ? 2 : 1;
; #pragma unroll 1
;     for (int half = 0; half < nhalf; ++half) {
; #pragma unroll
;     for (int i = 0; i < 4; ++i) *(LAS f32x4*)(Uh + (16 * i + utt) * 16 + ucc) = uh[i];
;     if (half + 1 < nhalf) {
; #pragma unroll
;         for (int i = 0; i < 4; ++i) uh[i] = *(const f32x4*)(ubuf + (size_t)(row0 + 64 + 16 * i + utt) * D + g * 16 + ucc); }
.LBB0_1460:
	s_lshr_b32 s6, s26, 4
	s_and_b32 s6, s6, 12
	s_ashr_i32 s7, s26, 8
	s_or_b32 s6, s6, s7
	s_ashr_i32 s52, s6, 3
	s_lshl_b32 s6, s6, 3
	s_and_b32 s6, s6, 56
	s_add_i32 s54, s6, s67
	s_lshl_b32 s6, s52, 13
	s_lshl_b32 s7, s54, 7
	s_add_i32 s7, s7, s6
	v_or_b32_e32 v60, s7, v165
	s_lshl_b32 s28, s4, 6
	v_ashrrev_i32_e32 v61, 31, v60
	v_lshl_add_u64 v[62:63], v[50:51], 0, s[28:29]
	s_cmp_eq_u32 s99, 1
	s_cbranch_scc1 .Lsa_have
	v_or_b32_e32 v34, 16, v60
	s_waitcnt vmcnt(2)
	v_or_b32_e32 v40, 32, v60
	v_or_b32_e32 v42, 48, v60
	v_ashrrev_i32_e32 v35, 31, v34
	v_ashrrev_i32_e32 v41, 31, v40
	v_ashrrev_i32_e32 v43, 31, v42
	v_lshlrev_b64 v[32:33], 12, v[60:61]
	v_lshlrev_b64 v[34:35], 12, v[34:35]
	v_lshlrev_b64 v[40:41], 12, v[40:41]
	v_lshlrev_b64 v[42:43], 12, v[42:43]
	v_lshl_add_u64 v[32:33], v[62:63], 0, v[32:33]
	v_lshl_add_u64 v[36:37], v[62:63], 0, v[34:35]
	v_lshl_add_u64 v[40:41], v[62:63], 0, v[40:41]
	s_waitcnt vmcnt(1)
	v_lshl_add_u64 v[44:45], v[62:63], 0, v[42:43]
	global_load_dwordx4 v[32:35], v[32:33], off
	s_nop 0
	global_load_dwordx4 v[36:39], v[36:37], off
	s_nop 0
	global_load_dwordx4 v[40:43], v[40:41], off
	s_nop 0
	global_load_dwordx4 v[44:47], v[44:45], off
.Lsa_have:
	v_or_b32_e32 v54, 64, v60
	v_or_b32_e32 v56, 0x50, v60
	v_or_b32_e32 v58, 0x60, v60
	v_or_b32_e32 v60, 0x70, v60
	v_ashrrev_i32_e32 v55, 31, v54
	v_ashrrev_i32_e32 v57, 31, v56
	v_ashrrev_i32_e32 v59, 31, v58
	v_ashrrev_i32_e32 v61, 31, v60
	v_lshlrev_b64 v[54:55], 12, v[54:55]
	v_lshlrev_b64 v[56:57], 12, v[56:57]
	v_lshlrev_b64 v[58:59], 12, v[58:59]
	v_lshlrev_b64 v[60:61], 12, v[60:61]
	v_mov_b32_e32 v49, v48
	v_lshl_add_u64 v[54:55], v[62:63], 0, v[54:55]
	v_lshl_add_u64 v[56:57], v[62:63], 0, v[56:57]
	v_lshl_add_u64 v[58:59], v[62:63], 0, v[58:59]
	v_lshl_add_u64 v[60:61], v[62:63], 0, v[60:61]
	v_mov_b32_e32 v62, v52
	v_mov_b32_e32 v63, v52
	v_mov_b32_e32 v64, v53
	v_mov_b32_e32 v65, v53
	v_pk_mov_b32 v[66:67], v[52:53], v[52:53] op_sel:[1,0]
	s_mov_b64 s[58:59], -1
	v_mov_b64_e32 v[68:69], v[48:49]
.LBB0_1461:
	s_xor_b64 s[56:57], s[58:59], -1
	s_and_b64 vcc, exec, s[56:57]
	s_waitcnt vmcnt(3)
	ds_write_b128 v73, v[32:35]
	s_waitcnt vmcnt(2)
	ds_write_b128 v73, v[36:39] offset:1024
	s_waitcnt vmcnt(1)
	ds_write_b128 v73, v[40:43] offset:2048
	s_waitcnt vmcnt(0)
	ds_write_b128 v73, v[44:47] offset:3072
	s_cbranch_vccnz .Lsa_pf
	global_load_dwordx4 v[32:35], v[54:55], off
	global_load_dwordx4 v[36:39], v[56:57], off
	global_load_dwordx4 v[40:43], v[58:59], off
	global_load_dwordx4 v[44:47], v[60:61], off
	s_branch .LBB0_1463
.Lsa_pf:
	s_mov_b32 s99, 0
	s_add_i32 s100, s26, s66
	s_cmpk_gt_i32 s100, 0x3ff
	s_cbranch_scc1 .LBB0_1463
	s_mov_b32 s99, 1
	s_mov_b32 s100, 0x3c0000
	s_mov_b32 s101, 0
	v_lshl_add_u64 v[244:245], v[54:55], 0, s[100:101]
	v_lshl_add_u64 v[246:247], v[56:57], 0, s[100:101]
	v_lshl_add_u64 v[248:249], v[58:59], 0, s[100:101]
	v_lshl_add_u64 v[250:251], v[60:61], 0, s[100:101]
	global_load_dwordx4 v[32:35], v[244:245], off
	global_load_dwordx4 v[36:39], v[246:247], off
	global_load_dwordx4 v[40:43], v[248:249], off
	global_load_dwordx4 v[44:47], v[250:251], off

; template <bool PROJECT> ...
;     ...
;     for (int tl = 0; tl < 4; ++tl) {
;         const int t0 = 64 * half + 16 * tl; if (t0 >= ntok) break;
;         const int nsub = (ntok - t0) < 16 ? (ntok - t0) : 16;
;         LAS float* Ul = Uh + tl * 256;
;         {
;             const f32x4 a0 = *(const LAS f32x4*)(Ul + c * 16 + c0), a1 = *(const LAS f32x4*)(Ul + c * 16 + c0 + 4);
;             u32x4 wh; wh.x = cvt_pk_bf16(a0[0], a0[1]); wh.y = cvt_pk_bf16(a0[2], a0[3]); wh.z = cvt_pk_bf16(a1[0], a1[1]); wh.w = cvt_pk_bf16(a1[2], a1[3]);
;             u32x4 wl;
;             wl.x = cvt_pk_bf16(a0[0] - __uint_as_float(wh.x << 16), a0[1] - __uint_as_float(wh.x & 0xffff0000u)); wl.y = cvt_pk_bf16(a0[2] - __uint_as_float(wh.y << 16), a0[3] - __uint_as_float(wh.y & 0xffff0000u));
;             wl.z = cvt_pk_bf16(a1[0] - __uint_as_float(wh.z << 16), a1[1] - __uint_as_float(wh.z & 0xffff0000u)); wl.w = cvt_pk_bf16(a1[2] - __uint_as_float(wh.w << 16), a1[3] - __uint_as_float(wh.w & 0xffff0000u));
;             u32x4 wsel; wsel.x = part ? wl.x : wh.x; wsel.y = part ? wl.y : wh.y; wsel.z = part ? wl.z : wh.z; wsel.w = part ? wl.w : wh.w;
;             const bf16x8 aop = __builtin_bit_cast(bf16x8, wsel);
;             f32x4 br[4], bi[4];
; #pragma unroll
;             for (int i = 0; i < 4; ++i) {
;                 f32x4 zr = (f32x4){0.f, 0.f, 0.f, 0.f}, zi = zr;
;                 br[i] = __builtin_amdgcn_mfma_f32_16x16x32_bf16(aop, bop[0][i], zr, 0, 0, 0); bi[i] = __builtin_amdgcn_mfma_f32_16x16x32_bf16(aop, bop[1][i], zi, 0, 0, 0);
;             }
;             asm volatile("s_nop 15\n\ts_nop 15\n\ts_nop 15\n\ts_nop 15" : "+v"(br[0]), "+v"(br[1]), "+v"(br[2]), "+v"(br[3]), "+v"(bi[0]), "+v"(bi[1]), "+v"(bi[2]), "+v"(bi[3]), "+v"(wsel));
; #pragma unroll
;             for (int i = 0; i < 4; ++i)
; #pragma unroll
;                 for (int j = 0; j < 4; ++j) *(LAS f32x2v*)(BUl + (4 * tq + j) * BU_PITCH + 2 * (16 * i + c)) = (f32x2v){br[i][j], bi[i][j]};
;             asm volatile("s_waitcnt lgkmcnt(0)" ::: "memory"); __builtin_amdgcn_wave_barrier();
;         }
;         {
;             float bur[16], bui[16];
; #pragma unroll
;             for (int t = 0; t < 16; ++t) { const f32x2v bu = *(const LAS f32x2v*)(BUl + t * BU_PITCH + 2 * lane); bur[t] = bu.x; bui[t] = bu.y; }
; #pragma unroll
;             for (int t = 0; t < 16; ++t) {
.LBB0_1464:
	v_add_u32_e32 v49, s28, v74
	ds_read_b128 v[76:79], v49
	ds_read_b128 v[80:83], v49 offset:16
	s_addk_i32 s28, 0x400
	s_cmpk_eq_i32 s28, 0x1000
	s_waitcnt lgkmcnt(0)
	v_cvt_pk_bf16_f32 v49, v76, v77
	s_nop 0
	v_lshlrev_b32_e32 v86, 16, v49
	v_sub_f32_e32 v76, v76, v86
	v_and_b32_e32 v86, 0xffff0000, v49
	v_sub_f32_e32 v77, v77, v86
	v_cvt_pk_bf16_f32 v75, v78, v79
	v_cvt_pk_bf16_f32 v84, v80, v81
	v_cvt_pk_bf16_f32 v85, v82, v83
	v_cvt_pk_bf16_f32 v76, v76, v77
	s_nop 0
	v_lshlrev_b32_e32 v77, 16, v75
	v_sub_f32_e32 v77, v78, v77
	v_and_b32_e32 v78, 0xffff0000, v75
	v_sub_f32_e32 v78, v79, v78
	v_cvt_pk_bf16_f32 v77, v77, v78
	v_lshlrev_b32_e32 v78, 16, v84
	v_and_b32_e32 v79, 0xffff0000, v84
	v_sub_f32_e32 v78, v80, v78
	v_sub_f32_e32 v79, v81, v79
	v_cvt_pk_bf16_f32 v78, v78, v79
	v_lshlrev_b32_e32 v79, 16, v85
	v_sub_f32_e32 v79, v82, v79
	v_and_b32_e32 v80, 0xffff0000, v85
	v_sub_f32_e32 v80, v83, v80
	v_cvt_pk_bf16_f32 v79, v79, v80
	v_cndmask_b32_e64 v76, v76, v49, s[46:47]
	v_cndmask_b32_e64 v77, v77, v75, s[46:47]
	v_cndmask_b32_e64 v78, v78, v84, s[46:47]
	v_cndmask_b32_e64 v79, v79, v85, s[46:47]
	v_add_u32_e32 v49, v169, v171
	v_add_u32_e32 v75, 0x2000, v49
	v_mfma_f32_16x16x32_bf16 v[80:83], v[76:79], v[0:3], 0
	v_add_u32_e32 v49, 0x2800, v49
	v_mfma_f32_16x16x32_bf16 v[84:87], v[76:79], v[4:7], 0
	v_mfma_f32_16x16x32_bf16 v[88:91], v[76:79], v[8:11], 0
	v_mfma_f32_16x16x32_bf16 v[92:95], v[76:79], v[12:15], 0
	v_mfma_f32_16x16x32_bf16 v[96:99], v[76:79], v[16:19], 0
	v_mfma_f32_16x16x32_bf16 v[100:103], v[76:79], v[20:23], 0
	v_mfma_f32_16x16x32_bf16 v[104:107], v[76:79], v[24:27], 0
	v_mfma_f32_16x16x32_bf16 v[108:111], v[76:79], v[28:31], 0
	s_nop 7
	s_nop 0
	v_add_u32_e32 v76, v169, v171
	v_add_u32_e32 v76, 0x2100, v76
	v_add_u32_e32 v77, 0x410, v76
	ds_write2_b32 v76, v80, v84 offset0:0 offset1:1
	ds_write2_b32 v76, v81, v85 offset0:130 offset1:131
	ds_write2_b32 v77, v82, v86 offset0:0 offset1:1
	ds_write2_b32 v77, v83, v87 offset0:130 offset1:131
	ds_write2_b32 v76, v88, v92 offset0:32 offset1:33
	ds_write2_b32 v76, v89, v93 offset0:162 offset1:163
	ds_write2_b32 v77, v90, v94 offset0:32 offset1:33
	ds_write2_b32 v77, v91, v95 offset0:162 offset1:163
	ds_write2_b32 v76, v96, v100 offset0:64 offset1:65
	ds_write2_b32 v76, v97, v101 offset0:194 offset1:195
	ds_write2_b32 v77, v98, v102 offset0:64 offset1:65
	ds_write2_b32 v77, v99, v103 offset0:194 offset1:195
	ds_write2_b32 v76, v104, v108 offset0:96 offset1:97
	ds_write2_b32 v76, v105, v109 offset0:226 offset1:227
	ds_write2_b32 v77, v106, v110 offset0:96 offset1:97
	ds_write2_b32 v77, v107, v111 offset0:226 offset1:227
	v_add_u32_e32 v49, s27, v166
	v_add_u32_e32 v75, 0x2000, v49
	s_waitcnt lgkmcnt(0)
	ds_read2_b64 v[76:79], v75 offset0:32 offset1:97
	ds_read2_b64 v[80:83], v75 offset0:162 offset1:227
	v_add_u32_e32 v75, 0x2800, v49
	ds_read2_b64 v[84:87], v75 offset0:36 offset1:101
	ds_read2_b64 v[88:91], v75 offset0:166 offset1:231
	v_add_u32_e32 v75, 0x3000, v49
	ds_read2_b64 v[92:95], v75 offset0:40 offset1:105
	ds_read2_b64 v[96:99], v75 offset0:170 offset1:235
	v_add_u32_e32 v49, 0x3800, v49
	ds_read2_b64 v[100:103], v49 offset0:44 offset1:109
	ds_read2_b64 v[104:107], v49 offset0:174 offset1:239
	s_waitcnt lgkmcnt(7)
	v_fma_f32 v108, -v53, v69, v76
	v_fma_f32 v109, v53, v68, v77
	v_fmac_f32_e32 v108, v52, v68
	v_fmac_f32_e32 v109, v52, v69
	v_fma_f32 v68, -v53, v109, v78
	v_fma_f32 v69, v53, v108, v79
	v_fmac_f32_e32 v68, v52, v108
	v_fmac_f32_e32 v69, v52, v109
	s_waitcnt lgkmcnt(6)
	v_fma_f32 v108, -v53, v69, v80
	v_fma_f32 v109, v53, v68, v81
	v_fmac_f32_e32 v108, v52, v68
	v_fmac_f32_e32 v109, v52, v69
	v_fma_f32 v68, -v53, v109, v82
	v_fma_f32 v69, v53, v108, v83
	v_fmac_f32_e32 v68, v52, v108
	v_fmac_f32_e32 v69, v52, v109
	s_waitcnt lgkmcnt(5)
	v_fma_f32 v108, -v53, v69, v84
	v_fma_f32 v109, v53, v68, v85
	v_fmac_f32_e32 v108, v52, v68
	v_fmac_f32_e32 v109, v52, v69
	v_fma_f32 v68, -v53, v109, v86
	v_fma_f32 v69, v53, v108, v87
	v_fmac_f32_e32 v68, v52, v108
	v_fmac_f32_e32 v69, v52, v109
	s_waitcnt lgkmcnt(4)
	v_fma_f32 v108, -v53, v69, v88
	v_fma_f32 v109, v53, v68, v89
	v_fmac_f32_e32 v108, v52, v68
	v_fmac_f32_e32 v109, v52, v69
	v_fma_f32 v68, -v53, v109, v90
	v_fma_f32 v69, v53, v108, v91
	v_fmac_f32_e32 v68, v52, v108
	v_fmac_f32_e32 v69, v52, v109
	s_waitcnt lgkmcnt(3)
	v_fma_f32 v108, -v53, v69, v92
	v_fma_f32 v109, v53, v68, v93
	v_fmac_f32_e32 v108, v52, v68
	v_fmac_f32_e32 v109, v52, v69
	v_fma_f32 v68, -v53, v109, v94
	v_fma_f32 v69, v53, v108, v95
	v_fmac_f32_e32 v68, v52, v108
	v_fmac_f32_e32 v69, v52, v109
	s_waitcnt lgkmcnt(2)
	v_fma_f32 v108, -v53, v69, v96
	v_fma_f32 v109, v53, v68, v97
	v_fmac_f32_e32 v108, v52, v68
	v_fmac_f32_e32 v109, v52, v69
	v_fma_f32 v68, -v53, v109, v98
	v_fma_f32 v69, v53, v108, v99
	v_fmac_f32_e32 v68, v52, v108
	v_fmac_f32_e32 v69, v52, v109
	s_waitcnt lgkmcnt(1)
	v_fma_f32 v108, -v53, v69, v100
	v_fma_f32 v109, v53, v68, v101
	v_fmac_f32_e32 v108, v52, v68
	v_fmac_f32_e32 v109, v52, v69
	v_fma_f32 v68, -v53, v109, v102
	v_fma_f32 v69, v53, v108, v103
	v_fmac_f32_e32 v68, v52, v108
	v_fmac_f32_e32 v69, v52, v109
	s_waitcnt lgkmcnt(0)
	v_fma_f32 v108, -v53, v69, v104
	v_fma_f32 v109, v53, v68, v105
	v_fmac_f32_e32 v108, v52, v68
	v_fmac_f32_e32 v109, v52, v69
	v_fma_f32 v68, -v53, v109, v106
	v_fma_f32 v69, v53, v108, v107
	v_fmac_f32_e32 v68, v52, v108
	v_fmac_f32_e32 v69, v52, v109
	s_cbranch_scc0 .LBB0_1464
	s_mov_b64 s[58:59], 0
	s_and_b64 vcc, exec, s[56:57]
	s_cbranch_vccz .LBB0_1461
	s_ashr_i32 s53, s52, 31
	s_mov_b32 s55, s29
	s_lshl_b64 s[6:7], s[52:53], 12
	s_lshl_b64 s[30:31], s[54:55], 6
	s_add_u32 s6, s30, s6
	s_addc_u32 s7, s31, s7
	s_or_b32 s6, s6, s4
	s_lshl_b64 s[6:7], s[6:7], 9
	s_add_i32 s26, s26, s66
	s_waitcnt vmcnt(3)
	v_lshl_add_u64 v[252:253], v[174:175], 0, s[6:7]
	s_cmpk_gt_i32 s26, 0x3ff
	global_store_dwordx2 v[252:253], v[68:69], off
	s_cbranch_scc0 .LBB0_1458

; __global__ void __launch_bounds__(NTHREADS, 2) fwd_megakernel(Args a) {
;     ...
;         bf16x8 bop[2][4], cop[4]; float lre = 0.f, lim = 0.f, dv = 0.f; int gcur = -1, bprev = -1, kprev = -100;
;         float hre = 0.f, him = 0.f, pre = 0.f, pim = 0.f;
; #pragma unroll 1
;         for (int it = blockIdx.x; it < 1024; it += gridDim.x) {
;             const int g = it & 63, cc = it >> 6, ccp = ((cc & 3) << 2) | (cc >> 2), b = ccp >> 3, co = ccp & 7, k = co * 8 + wave;
.LBB0_1526:
	s_or_b64 exec, exec, s[28:29]
	s_andn2_b64 vcc, exec, s[38:39]
	s_waitcnt lgkmcnt(0)
	s_barrier
	s_cbranch_vccnz .LBB0_1548
	s_load_dwordx2 s[4:5], s[0:1], 0xc8
	s_load_dwordx4 s[56:59], s[0:1], 0x98
	v_mov_b32_e32 v181, 0
	v_mov_b32_e32 v167, v181
	v_mul_i32_i24_e32 v2, 0xffffffc4, v161
	s_waitcnt lgkmcnt(0)
	s_add_u32 s38, s4, 0x4b80000
	s_addc_u32 s39, s5, 0
	s_load_dwordx2 s[4:5], s[0:1], 0xd0
	v_mov_b32_e32 v180, v181
	s_mov_b32 s41, 0
	v_lshl_or_b32 v202, s67, 7, v150
	s_movk_i32 s40, 0xff9c
	s_waitcnt lgkmcnt(0)
	v_lshl_add_u64 v[0:1], s[4:5], 0, v[166:167]
	s_mov_b64 s[4:5], 0x150fc000
	v_lshl_add_u64 v[182:183], v[0:1], 0, s[4:5]
	v_lshlrev_b32_e32 v1, 1, v192
	v_add_u32_e32 v0, s42, v70
	v_and_b32_e32 v1, 32, v1
	v_add3_u32 v167, v0, v1, 0
	v_add3_u32 v0, v2, s42, v60
	v_add3_u32 v201, v0, v70, 0
	s_mov_b32 s26, -1
	s_mov_b32 s5, s2
	s_mov_b32 s30, -1
	s_mov_b32 s42, s2
	v_mov_b32_e32 v203, 0
	v_mov_b64_e32 v[186:187], v[180:181]
	v_mov_b64_e32 v[184:185], v[180:181]
	v_mov_b32_e32 v188, v181
	v_mov_b32_e32 v189, v181
	s_mov_b32 s99, 0
	s_branch .LBB0_1529

; template <bool PROJECT> ...
;     ...
;     const int utt = lane >> 2, ucc = (lane & 3) * 4;
;     f32x4 uh[4];
; #pragma unroll
;     for (int i = 0; i < 4; ++i) { uh[i] = (f32x4){0.f, 0.f, 0.f, 0.f}; if (16 * i + utt < ntok) uh[i] = *(const f32x4*)(ubuf + (size_t)(row0 + 16 * i + utt) * D + g * 16 + ucc); }
.LBB0_1539:
	s_lshl_b32 s6, s54, 13
	s_lshl_b32 s7, s44, 7
	s_add_i32 s7, s7, s6
	v_or_b32_e32 v206, s7, v165
	v_ashrrev_i32_e32 v207, 31, v206
	v_lshl_add_u64 v[208:209], v[180:181], 2, v[176:177]
	s_cmp_eq_u32 s99, 1
	s_cbranch_scc1 .Lsc_have
	v_or_b32_e32 v2, 16, v206
	v_lshlrev_b64 v[0:1], 12, v[206:207]
	v_ashrrev_i32_e32 v3, 31, v2
	v_lshl_add_u64 v[0:1], v[208:209], 0, v[0:1]
	v_lshlrev_b64 v[2:3], 12, v[2:3]
	v_lshl_add_u64 v[2:3], v[208:209], 0, v[2:3]
	global_load_dwordx4 v[96:99], v[0:1], off
	global_load_dwordx4 v[100:103], v[2:3], off
	v_or_b32_e32 v0, 32, v206
	v_ashrrev_i32_e32 v1, 31, v0
	v_or_b32_e32 v2, 48, v206
	v_lshlrev_b64 v[0:1], 12, v[0:1]
	v_ashrrev_i32_e32 v3, 31, v2
	v_lshl_add_u64 v[0:1], v[208:209], 0, v[0:1]
	v_lshlrev_b64 v[2:3], 12, v[2:3]
	v_lshl_add_u64 v[2:3], v[208:209], 0, v[2:3]
	global_load_dwordx4 v[104:107], v[0:1], off
	global_load_dwordx4 v[108:111], v[2:3], off
	s_branch .Lsc_go

; #define LAS __attribute__((address_space(3)))
; template <bool PROJECT> ...
;     ...
;     const int utt = lane >> 2, ucc = (lane & 3) * 4;
;     f32x4 uh[4];
; #pragma unroll
;     for (int i = 0; i < 4; ++i) { uh[i] = (f32x4){0.f, 0.f, 0.f, 0.f}; if (16 * i + utt < ntok) uh[i] = *(const f32x4*)(ubuf + (size_t)(row0 + 16 * i + utt) * D + g * 16 + ucc); }
;     const int nhalf = ntok > 64 ? 2 : 1;
; #pragma unroll 1
;     for (int half = 0; half < nhalf; ++half) {
; #pragma unroll
;     for (int i = 0; i < 4; ++i) *(LAS f32x4*)(Uh + (16 * i + utt) * 16 + ucc) = uh[i];
;     if (half + 1 < nhalf) {
; #pragma unroll
;         for (int i = 0; i < 4; ++i) uh[i] = *(const f32x4*)(ubuf + (size_t)(row0 + 64 + 16 * i + utt) * D + g * 16 + ucc); }
.Lsc_go:
	v_mov_b32_e32 v28, v112
	v_or_b32_e32 v112, 64, v206
	v_mov_b32_e32 v29, v113
	v_ashrrev_i32_e32 v113, 31, v112
	v_lshlrev_b64 v[112:113], 12, v[112:113]
	v_mov_b32_e32 v15, v119
	v_mov_b32_e32 v14, v118
	v_lshl_add_u64 v[118:119], v[208:209], 0, v[112:113]
	v_or_b32_e32 v112, 0x50, v206
	v_ashrrev_i32_e32 v113, 31, v112
	v_lshlrev_b64 v[112:113], 12, v[112:113]
	v_mov_b32_e32 v25, v121
	v_mov_b32_e32 v24, v120
	v_lshl_add_u64 v[120:121], v[208:209], 0, v[112:113]
	v_or_b32_e32 v112, 0x60, v206
	v_ashrrev_i32_e32 v113, 31, v112
	v_lshlrev_b64 v[112:113], 12, v[112:113]
	v_mov_b32_e32 v27, v123
	v_mov_b32_e32 v26, v122
	v_lshl_add_u64 v[122:123], v[208:209], 0, v[112:113]
	v_or_b32_e32 v112, 0x70, v206
	s_and_b32 s4, s4, 7
	v_ashrrev_i32_e32 v113, 31, v112
	s_lshl_b32 s4, s4, 10
	v_mov_b64_e32 v[186:187], v[190:191]
	v_lshlrev_b64 v[112:113], 12, v[112:113]
	s_or_b32 s4, s4, s6
	v_mov_b32_e32 v3, v147
	v_mov_b32_e32 v2, v146
	v_mov_b32_e32 v1, v145
	v_mov_b32_e32 v0, v144
	v_mov_b32_e32 v7, v135
	v_mov_b32_e32 v6, v134
	v_mov_b32_e32 v5, v133
	v_mov_b32_e32 v4, v132
	v_mov_b32_e32 v11, v127
	v_mov_b32_e32 v10, v126
	v_mov_b32_e32 v9, v125
	v_mov_b32_e32 v8, v124
	v_mov_b32_e32 v13, v117
	v_mov_b32_e32 v12, v116
	v_mov_b32_e32 v19, v139
	v_mov_b32_e32 v18, v138
	v_mov_b32_e32 v17, v137
	v_mov_b32_e32 v16, v136
	v_mov_b32_e32 v23, v131
	v_mov_b32_e32 v22, v130
	v_mov_b32_e32 v21, v129
	v_mov_b32_e32 v20, v128
	v_mov_b32_e32 v31, v115
	v_mov_b32_e32 v30, v114
	v_mov_b32_e32 v35, v159
	v_mov_b32_e32 v34, v158
	v_mov_b32_e32 v33, v157
	v_mov_b32_e32 v32, v156
	s_waitcnt vmcnt(7)
	v_mov_b32_e32 v39, v155
	v_mov_b32_e32 v38, v154
	v_mov_b32_e32 v37, v153
	v_mov_b32_e32 v36, v152
	s_waitcnt vmcnt(6)
	v_mov_b32_e32 v43, v151
	v_mov_b32_e32 v42, v150
	v_mov_b32_e32 v41, v149
	v_mov_b32_e32 v40, v148
	s_waitcnt vmcnt(5)
	v_mov_b32_e32 v47, v143
	v_mov_b32_e32 v46, v142
	v_mov_b32_e32 v45, v141
	v_mov_b32_e32 v44, v140
	v_mov_b32_e32 v203, v204
	v_lshl_add_u64 v[116:117], v[180:181], 1, v[178:179]
	v_lshl_add_u64 v[124:125], v[208:209], 0, v[112:113]
	v_mov_b32_e32 v126, v186
	v_mov_b32_e32 v127, v186
	v_mov_b32_e32 v128, v187
	v_mov_b32_e32 v129, v187
	v_pk_mov_b32 v[130:131], v[186:187], v[186:187] op_sel:[1,0]
	v_add_u32_e32 v132, s4, v202
	s_mov_b32 s4, 0
	s_mov_b64 s[28:29], 0
	s_mov_b64 s[48:49], -1
.LBB0_1540:
	s_andn2_b64 vcc, exec, s[48:49]
	s_waitcnt vmcnt(3)
	ds_write_b128 v198, v[96:99]
	s_waitcnt vmcnt(2)
	ds_write_b128 v198, v[100:103] offset:1024
	s_waitcnt vmcnt(1)
	ds_write_b128 v198, v[104:107] offset:2048
	s_waitcnt vmcnt(0)
	ds_write_b128 v198, v[108:111] offset:3072
	s_cbranch_vccnz .Lsc_pf
	global_load_dwordx4 v[96:99], v[118:119], off
	global_load_dwordx4 v[100:103], v[120:121], off
	global_load_dwordx4 v[104:107], v[122:123], off
	global_load_dwordx4 v[108:111], v[124:125], off
	s_branch .LBB0_1542
.Lsc_pf:
	s_mov_b32 s99, 0
	s_add_i32 s100, s42, s66
	s_cmpk_gt_i32 s100, 0x3ff
	s_cbranch_scc1 .LBB0_1542
	s_mov_b32 s99, 1
	s_mov_b32 s100, 0x3c0000
	s_mov_b32 s101, 0
	v_lshl_add_u64 v[244:245], v[118:119], 0, s[100:101]
	v_lshl_add_u64 v[246:247], v[120:121], 0, s[100:101]
	v_lshl_add_u64 v[248:249], v[122:123], 0, s[100:101]
	v_lshl_add_u64 v[250:251], v[124:125], 0, s[100:101]
	global_load_dwordx4 v[96:99], v[244:245], off
	global_load_dwordx4 v[100:103], v[246:247], off
	global_load_dwordx4 v[104:107], v[248:249], off
	global_load_dwordx4 v[108:111], v[250:251], off
